# scan: ISSUE back into the MFMA shadow of the merged stage (chunk c+3), COMMIT arithmetic stays at stage-Y start with exact vmcnt(14)
# baseline (speedup 1.0000x reference)
.Lsx0_c:
	s_or_b64 exec, exec, s[2:3]
	v_mov_b32_e32 v22, 0
	v_mov_b32_e32 v23, 0
	v_mov_b32_e32 v24, 0
	v_mov_b32_e32 v25, 0
	s_and_saveexec_b64 s[2:3], s[56:57]
	s_cbranch_execz .LBB0_403
	ds_read_b128 v[48:51], v174
	ds_read_b128 v[60:63], v192 offset:49152
	ds_read_b128 v[52:55], v174 offset:64
	ds_read_b128 v[64:67], v192 offset:49216
	ds_read_b128 v[56:59], v175
	ds_read_b128 v[68:71], v199
	ds_read_b128 v[72:75], v192 offset:58368
	ds_read_b128 v[76:79], v192 offset:58432
	ds_read_b128 v[80:83], v151
	ds_read_b128 v[84:87], v151 offset:16
	ds_read_b128 v[88:91], v151 offset:32
	ds_read_b128 v[92:95], v151 offset:48
	s_waitcnt lgkmcnt(10)
	v_mfma_f32_16x16x32_bf16 v[30:33], v[48:51], v[60:63], 0
	s_waitcnt lgkmcnt(8)
	v_mfma_f32_16x16x32_bf16 v[30:33], v[52:55], v[64:67], v[30:33]
	s_waitcnt lgkmcnt(6)
	v_mfma_f32_16x16x32_bf16 v[30:33], v[56:59], v[68:71], v[30:33]
	s_waitcnt lgkmcnt(5)
	v_mfma_f32_16x16x32_bf16 v[22:25], v[48:51], v[72:75], 0
	s_waitcnt lgkmcnt(4)
	v_mfma_f32_16x16x32_bf16 v[22:25], v[52:55], v[76:79], v[22:25]
	s_cmp_eq_u32 s36, 0
	s_cbranch_scc1 .Lis0b
	s_cmp_gt_u32 s36, 62
	s_cbranch_scc1 .Lis0b
	s_add_i32 s24, s19, 0xffffffc0
	s_add_i32 s25, s21, 0x30
	s_and_b64 s[98:99], s[12:13], exec
	s_cselect_b32 s24, s25, s24
	v_lshl_add_u32 v194, s24, 6, v183
	v_lshlrev_b32_e32 v112, 1, v194
	global_load_dword v5, v112, s[44:45]
	global_load_dword v207, v112, s[44:45] offset:-1024
	global_load_dword v6, v112, s[42:43]
	global_load_dword v208, v112, s[42:43] offset:-1024
	global_load_dword v7, v112, s[0:1]
	global_load_dword v209, v112, s[0:1] offset:-1024
	global_load_dword v8, v112, s[34:35]
	global_load_dword v210, v112, s[34:35] offset:-1024
	global_load_dword v9, v112, s[76:77]
	global_load_dword v211, v112, s[76:77] offset:-1024
	v_add_u32_e32 v194, s24, v184
	v_lshlrev_b32_e32 v114, 2, v194
	global_load_dword v110, v114, s[40:41]
	global_load_dword v212, v114, s[40:41] offset:-32

.Lpq0_end:
	s_waitcnt lgkmcnt(0)
	s_barrier
	v_add_u32_e32 v200, v146, v145
	v_add_u32_e32 v112, v156, v163
	ds_read_b128 v[48:51], v180
	ds_read_b128 v[52:55], v112 offset:62976
	ds_read_b128 v[56:59], v112 offset:64256
	v_sub_u32_e32 v113, v164, v143
	v_mad_u32_u24 v113, v145, 5, v113
	v_add_u32_e32 v113, 0x18d00, v113
	ds_read_b128 v[88:91], v113
	ds_read_b128 v[92:95], v113 offset:64
	s_and_b64 s[98:99], s[56:57], exec
	s_cbranch_scc0 .Lcp0
	s_cmp_gt_u32 s36, 62
	s_cbranch_scc1 .Lcp0
	s_cmp_eq_u32 s36, 0
	s_cbranch_scc1 .Lvw0
	s_waitcnt vmcnt(14)
	s_branch .Lvx0

.Lvx0:
	v_lshlrev_b32_e32 v136, 16, v1
	v_and_b32_e32 v137, 0xffff0000, v1
	v_pk_mul_f32 v[124:125], v[102:103], v[136:137]
	v_lshlrev_b32_e32 v126, 16, v3
	v_pk_mul_f32 v[124:125], v[108:109], v[124:125] op_sel_hi:[0,1]
	v_and_b32_e32 v127, 0xffff0000, v3
	v_lshlrev_b32_e32 v130, 16, v4
	v_and_b32_e32 v131, 0xffff0000, v4
	v_pk_add_f32 v[128:129], v[130:131], -1.0 op_sel_hi:[1,0]
	v_pk_mul_f32 v[130:131], v[130:131], v[124:125] neg_lo:[0,1] neg_hi:[0,1]
	v_pk_fma_f32 v[128:129], v[104:105], v[128:129], 1.0 op_sel_hi:[1,1,0]
	s_nop 0
	v_pk_mul_f32 v[128:129], v[128:129], v[136:137]
	v_lshlrev_b32_e32 v132, 16, v0
	v_and_b32_e32 v133, 0xffff0000, v0
	v_lshlrev_b32_e32 v134, 16, v2
	v_and_b32_e32 v135, 0xffff0000, v2
	v_lshlrev_b32_e32 v136, 16, v202
	v_and_b32_e32 v137, 0xffff0000, v202
	v_pk_mul_f32 v[214:215], v[102:103], v[136:137]
	v_lshlrev_b32_e32 v216, 16, v204
	v_pk_mul_f32 v[214:215], v[206:207], v[214:215] op_sel_hi:[0,1]
	v_and_b32_e32 v217, 0xffff0000, v204
	v_lshlrev_b32_e32 v228, 16, v205
	v_and_b32_e32 v229, 0xffff0000, v205
	v_pk_add_f32 v[218:219], v[228:229], -1.0 op_sel_hi:[1,0]
	v_pk_mul_f32 v[228:229], v[228:229], v[214:215] neg_lo:[0,1] neg_hi:[0,1]
	v_pk_fma_f32 v[218:219], v[104:105], v[218:219], 1.0 op_sel_hi:[1,1,0]
	s_nop 0
	v_pk_mul_f32 v[218:219], v[218:219], v[136:137]
	v_lshlrev_b32_e32 v230, 16, v201
	v_and_b32_e32 v231, 0xffff0000, v201
	v_lshlrev_b32_e32 v232, 16, v203
	v_and_b32_e32 v233, 0xffff0000, v203

.Lsx1_c:
	s_or_b64 exec, exec, s[74:75]
	v_mov_b32_e32 v22, 0
	v_mov_b32_e32 v23, 0
	v_mov_b32_e32 v24, 0
	v_mov_b32_e32 v25, 0
	s_and_saveexec_b64 s[74:75], s[56:57]
	s_cbranch_execz .LBB0_432
	ds_read_b128 v[48:51], v174
	ds_read_b128 v[60:63], v192 offset:51456
	ds_read_b128 v[52:55], v174 offset:64
	ds_read_b128 v[64:67], v192 offset:51520
	ds_read_b128 v[56:59], v175 offset:5120
	ds_read_b128 v[68:71], v199
	ds_read_b128 v[72:75], v192 offset:60672
	ds_read_b128 v[76:79], v192 offset:60736
	ds_read_b128 v[80:83], v151
	ds_read_b128 v[84:87], v151 offset:16
	ds_read_b128 v[88:91], v151 offset:32
	ds_read_b128 v[92:95], v151 offset:48
	s_waitcnt lgkmcnt(10)
	v_mfma_f32_16x16x32_bf16 v[30:33], v[48:51], v[60:63], 0
	s_waitcnt lgkmcnt(8)
	v_mfma_f32_16x16x32_bf16 v[30:33], v[52:55], v[64:67], v[30:33]
	s_waitcnt lgkmcnt(6)
	v_mfma_f32_16x16x32_bf16 v[30:33], v[56:59], v[68:71], v[30:33]
	s_waitcnt lgkmcnt(5)
	v_mfma_f32_16x16x32_bf16 v[22:25], v[48:51], v[72:75], 0
	s_waitcnt lgkmcnt(4)
	v_mfma_f32_16x16x32_bf16 v[22:25], v[52:55], v[76:79], v[22:25]
	s_cmp_gt_u32 s36, 61
	s_cbranch_scc1 .Lis1bw
	s_add_i32 s24, s19, 0xffffffb0
	s_add_i32 s25, s21, 64
	s_and_b64 s[98:99], s[12:13], exec
	s_cselect_b32 s24, s25, s24
	v_lshl_add_u32 v194, s24, 6, v183
	v_lshlrev_b32_e32 v112, 1, v194
	global_load_dword v0, v112, s[44:45]
	global_load_dword v201, v112, s[44:45] offset:-1024
	global_load_dword v1, v112, s[42:43]
	global_load_dword v202, v112, s[42:43] offset:-1024
	global_load_dword v2, v112, s[0:1]
	global_load_dword v203, v112, s[0:1] offset:-1024
	global_load_dword v4, v112, s[76:77]
	global_load_dword v205, v112, s[76:77] offset:-1024
	global_load_dword v3, v112, s[34:35]
	global_load_dword v204, v112, s[34:35] offset:-1024
	v_add_u32_e32 v194, s24, v184
	v_lshlrev_b32_e32 v114, 2, v194
	global_load_dword v108, v114, s[40:41]
	global_load_dword v206, v114, s[40:41] offset:-32
	s_branch .Lis1b

.Lpq1_end:
	s_waitcnt lgkmcnt(0)
	s_barrier
	s_and_b64 s[24:25], s[46:47], s[2:3]
	ds_read_b128 v[48:51], v180 offset:5120
	ds_read_b128 v[52:55], v170 offset:5120
	ds_read_b128 v[56:59], v170 offset:6400
	v_sub_u32_e32 v113, v164, v143
	v_mad_u32_u24 v113, v145, 5, v113
	v_add_u32_e32 v113, 0x18e00, v113
	ds_read_b128 v[88:91], v113
	ds_read_b128 v[92:95], v113 offset:64
	s_and_b64 s[98:99], s[56:57], exec
	s_cbranch_scc0 .Lcp1
	s_cmp_gt_u32 s36, 62
	s_cbranch_scc1 .Lcp1
	s_cmp_eq_u32 s36, 0
	s_cbranch_scc1 .Lvw1
	s_cmp_gt_u32 s36, 61
	s_cbranch_scc1 .Lvw1
	s_waitcnt vmcnt(14)
	s_branch .Lvx1

.Lvx1:
	v_lshlrev_b32_e32 v136, 16, v6
	v_and_b32_e32 v137, 0xffff0000, v6
	v_pk_mul_f32 v[124:125], v[102:103], v[136:137]
	v_lshlrev_b32_e32 v126, 16, v8
	v_pk_mul_f32 v[124:125], v[110:111], v[124:125] op_sel_hi:[0,1]
	v_and_b32_e32 v127, 0xffff0000, v8
	v_lshlrev_b32_e32 v130, 16, v9
	v_and_b32_e32 v131, 0xffff0000, v9
	v_pk_add_f32 v[128:129], v[130:131], -1.0 op_sel_hi:[1,0]
	v_pk_mul_f32 v[130:131], v[130:131], v[124:125] neg_lo:[0,1] neg_hi:[0,1]
	v_pk_fma_f32 v[128:129], v[104:105], v[128:129], 1.0 op_sel_hi:[1,1,0]
	s_nop 0
	v_pk_mul_f32 v[128:129], v[128:129], v[136:137]
	v_lshlrev_b32_e32 v132, 16, v5
	v_and_b32_e32 v133, 0xffff0000, v5
	v_lshlrev_b32_e32 v134, 16, v7
	v_and_b32_e32 v135, 0xffff0000, v7
	v_lshlrev_b32_e32 v136, 16, v208
	v_and_b32_e32 v137, 0xffff0000, v208
	v_pk_mul_f32 v[214:215], v[102:103], v[136:137]
	v_lshlrev_b32_e32 v216, 16, v210
	v_pk_mul_f32 v[214:215], v[212:213], v[214:215] op_sel_hi:[0,1]
	v_and_b32_e32 v217, 0xffff0000, v210
	v_lshlrev_b32_e32 v228, 16, v211
	v_and_b32_e32 v229, 0xffff0000, v211
	v_pk_add_f32 v[218:219], v[228:229], -1.0 op_sel_hi:[1,0]
	v_pk_mul_f32 v[228:229], v[228:229], v[214:215] neg_lo:[0,1] neg_hi:[0,1]
	v_pk_fma_f32 v[218:219], v[104:105], v[218:219], 1.0 op_sel_hi:[1,1,0]
	s_nop 0
	v_pk_mul_f32 v[218:219], v[218:219], v[136:137]
	v_lshlrev_b32_e32 v230, 16, v207
	v_and_b32_e32 v231, 0xffff0000, v207
	v_lshlrev_b32_e32 v232, 16, v209
	v_and_b32_e32 v233, 0xffff0000, v209
